# LRU pass-1 gate stage: the 32 per-element LDS reads of the conv output issued as one batch after the gate MFMAs
# speedup vs baseline: 1.0077x; 1.0047x over previous
.LBB0_685:
	s_or_b64 exec, exec, s[12:13]
	s_nop 0
	v_lshrrev_b32_e32 v64, 1, v162
	v_and_b32_e32 v96, 32, v64
	v_or_b32_e32 v64, v96, v163
	v_and_b32_e32 v65, 0xffffff80, v162
	v_add_u32_e32 v97, s14, v65
	v_and_b32_e32 v65, 48, v162
	v_mul_u32_u24_e32 v64, 0x210, v64
	v_add3_u32 v64, v97, v65, v64
	s_waitcnt lgkmcnt(0)
	s_barrier
	ds_read_b128 v[80:83], v64
	ds_read_b128 v[84:87], v64 offset:64
	ds_read_b128 v[88:91], v64 offset:8448
	ds_read_b128 v[92:95], v64 offset:8512
	s_waitcnt lgkmcnt(3)
	v_mfma_f32_16x16x32_bf16 v[64:67], v[80:83], v[16:19], 0
	s_movk_i32 s12, 0x100
	v_cmp_gt_i32_e32 vcc, s12, v162
	s_waitcnt lgkmcnt(1)
	v_mfma_f32_16x16x32_bf16 v[16:19], v[88:91], v[16:19], 0
	v_mfma_f32_16x16x32_bf16 v[76:79], v[84:87], v[8:11], v[64:67]
	s_waitcnt lgkmcnt(0)
	v_mfma_f32_16x16x32_bf16 v[72:75], v[92:95], v[8:11], v[16:19]
	v_mfma_f32_16x16x32_bf16 v[8:11], v[80:83], v[4:7], 0
	v_mfma_f32_16x16x32_bf16 v[4:7], v[88:91], v[4:7], 0
	v_mfma_f32_16x16x32_bf16 v[68:71], v[84:87], v[0:3], v[8:11]
	v_mfma_f32_16x16x32_bf16 v[64:67], v[92:95], v[0:3], v[4:7]
	v_mfma_f32_16x16x32_bf16 v[0:3], v[80:83], v[24:27], 0
	v_mfma_f32_16x16x32_bf16 v[4:7], v[88:91], v[24:27], 0
	v_mfma_f32_16x16x32_bf16 v[24:27], v[84:87], v[56:59], v[0:3]
	v_mfma_f32_16x16x32_bf16 v[16:19], v[92:95], v[56:59], v[4:7]
	v_mfma_f32_16x16x32_bf16 v[0:3], v[80:83], v[48:51], 0
	v_mfma_f32_16x16x32_bf16 v[4:7], v[88:91], v[48:51], 0
	v_mfma_f32_16x16x32_bf16 v[8:11], v[84:87], v[60:63], v[0:3]
	v_mfma_f32_16x16x32_bf16 v[0:3], v[92:95], v[60:63], v[4:7]
	v_mfma_f32_16x16x32_bf16 v[4:7], v[80:83], v[40:43], 0
	v_mfma_f32_16x16x32_bf16 v[60:63], v[84:87], v[28:31], v[4:7]
	v_mfma_f32_16x16x32_bf16 v[4:7], v[80:83], v[20:23], 0
	v_mfma_f32_16x16x32_bf16 v[40:43], v[88:91], v[40:43], 0
	v_mfma_f32_16x16x32_bf16 v[20:23], v[88:91], v[20:23], 0
	v_mfma_f32_16x16x32_bf16 v[48:51], v[84:87], v[12:15], v[4:7]
	v_mfma_f32_16x16x32_bf16 v[4:7], v[80:83], v[52:55], 0
	v_mfma_f32_16x16x32_bf16 v[56:59], v[92:95], v[28:31], v[40:43]
	v_mfma_f32_16x16x32_bf16 v[40:43], v[92:95], v[12:15], v[20:23]
	v_mfma_f32_16x16x32_bf16 v[12:15], v[88:91], v[52:55], 0
	v_mfma_f32_16x16x32_bf16 v[28:31], v[84:87], v[44:47], v[4:7]
	v_mfma_f32_16x16x32_bf16 v[4:7], v[80:83], v[36:39], 0
	v_mul_f32_e32 v80, 0xbfb8aa3b, v174
	v_mul_f32_e32 v81, 0xbfb8aa3b, v175
	v_mfma_f32_16x16x32_bf16 v[36:39], v[88:91], v[36:39], 0
	v_mfma_f32_16x16x32_bf16 v[20:23], v[92:95], v[44:47], v[12:15]
	v_mfma_f32_16x16x32_bf16 v[12:15], v[84:87], v[32:35], v[4:7]
	v_mfma_f32_16x16x32_bf16 v[4:7], v[92:95], v[32:35], v[36:39]
	v_lshl_or_b32 v152, v177, 2, v96
	v_lshlrev_b32_e32 v153, 1, v163
	v_mul_u32_u24_e32 v152, 0x210, v152
	v_add3_u32 v152, v97, v153, v152
	ds_read_u16 v98, v152
	ds_read_u16 v99, v152 offset:32
	ds_read_u16 v100, v152 offset:528
	ds_read_u16 v101, v152 offset:1056
	ds_read_u16 v102, v152 offset:1584
	ds_read_u16 v103, v152 offset:8448
	ds_read_u16 v104, v152 offset:8976
	ds_read_u16 v105, v152 offset:9504
	ds_read_u16 v106, v152 offset:10032
	ds_read_u16 v107, v152 offset:560
	ds_read_u16 v108, v152 offset:1088
	ds_read_u16 v109, v152 offset:1616
	ds_read_u16 v110, v152 offset:8480
	ds_read_u16 v111, v152 offset:9008
	ds_read_u16 v112, v152 offset:9536
	ds_read_u16 v113, v152 offset:10064
	ds_read_u16 v114, v152 offset:64
	ds_read_u16 v115, v152 offset:10096
	ds_read_u16 v116, v152 offset:592
	ds_read_u16 v117, v152 offset:1120
	ds_read_u16 v118, v152 offset:1648
	ds_read_u16 v119, v152 offset:8512
	ds_read_u16 v142, v152 offset:9040
	ds_read_u16 v143, v152 offset:9568
	ds_read_u16 v144, v152 offset:96
	ds_read_u16 v145, v152 offset:624
	ds_read_u16 v146, v152 offset:10128
	ds_read_u16 v147, v152 offset:1152
	ds_read_u16 v148, v152 offset:1680
	ds_read_u16 v149, v152 offset:8544
	ds_read_u16 v150, v152 offset:9072
	ds_read_u16 v151, v152 offset:9600
	v_mul_f32_e32 v34, 0xbfb8aa3b, v176
	v_exp_f32_e32 v34, v34
	v_fmamk_f32 v35, v60, 0xbfb8aa3b, v81
	v_min_f32_e32 v35, 0x42700000, v35
	v_exp_f32_e32 v35, v35
	v_add_f32_e32 v34, 1.0, v34
	v_log_f32_e32 v34, v34
	v_lshl_or_b32 v32, v177, 2, v96
	v_add_f32_e32 v35, 1.0, v35
	v_lshlrev_b32_e32 v33, 1, v163
	v_mul_f32_e32 v34, 0x3f317218, v34
	v_mul_f32_e32 v55, 0xc138aa3b, v34
	v_fmamk_f32 v34, v76, 0xbfb8aa3b, v80
	v_min_f32_e32 v34, 0x42700000, v34
	v_exp_f32_e32 v34, v34
	s_nop 0
	v_add_f32_e32 v34, 1.0, v34
	v_mul_f32_e32 v36, v34, v35
	v_rcp_f32_e32 v36, v36
	s_nop 0
	v_mul_f32_e32 v35, v35, v36
	v_mul_f32_e32 v34, v34, v36
	v_mul_u32_u24_e32 v36, 0x210, v32
	v_add3_u32 v76, v97, v33, v36
	v_mov_b32_e32 v33, v98
	v_mov_b32_e32 v60, v99
	v_lshlrev_b32_e32 v32, 10, v32
	s_waitcnt lgkmcnt(0)
	v_lshlrev_b32_e32 v36, 16, v33
	v_fma_mixlo_f16 v33, v55, v35, 0
	v_cvt_f32_f16_e32 v35, v33
	v_and_b32_e32 v33, 0xffff, v33
	v_exp_f32_e32 v35, v35
	s_nop 0
	v_fma_f32 v35, -v35, v35, 1.0
	v_max_f32_e32 v35, 0, v35
	v_sqrt_f32_e32 v35, v35
	s_nop 0
	v_mul_f32_e32 v34, v34, v35
	v_mul_f32_e32 v34, v34, v36
	v_fmamk_f32 v35, v77, 0xbfb8aa3b, v80
	v_fmamk_f32 v36, v61, 0xbfb8aa3b, v81
	v_min_f32_e32 v35, 0x42700000, v35
	v_min_f32_e32 v36, 0x42700000, v36
	v_exp_f32_e32 v35, v35
	v_exp_f32_e32 v36, v36
	v_add_f32_e32 v35, 1.0, v35
	v_add_f32_e32 v36, 1.0, v36
	v_mul_f32_e32 v37, v35, v36
	v_rcp_f32_e32 v37, v37
	s_nop 0
	v_mul_f32_e32 v36, v36, v37
	v_mul_f32_e32 v37, v35, v37
	v_mov_b32_e32 v35, v100
	s_waitcnt lgkmcnt(0)
	v_lshlrev_b32_e32 v38, 16, v35
	v_fma_mixlo_f16 v35, v55, v36, 0
	v_cvt_f32_f16_e32 v36, v35
	v_exp_f32_e32 v36, v36
	s_nop 0
	v_fma_f32 v36, -v36, v36, 1.0
	v_max_f32_e32 v36, 0, v36
	v_sqrt_f32_e32 v36, v36
	s_nop 0
	v_mul_f32_e32 v36, v37, v36
	v_mul_f32_e32 v36, v36, v38
	v_fmamk_f32 v37, v78, 0xbfb8aa3b, v80
	v_fmamk_f32 v38, v62, 0xbfb8aa3b, v81
	v_min_f32_e32 v37, 0x42700000, v37
	v_min_f32_e32 v38, 0x42700000, v38
	v_exp_f32_e32 v37, v37
	v_exp_f32_e32 v38, v38
	v_add_f32_e32 v37, 1.0, v37
	v_add_f32_e32 v38, 1.0, v38
	v_mul_f32_e32 v39, v37, v38
	v_rcp_f32_e32 v39, v39
	s_nop 0
	v_mul_f32_e32 v38, v38, v39
	v_mul_f32_e32 v39, v37, v39
	v_mov_b32_e32 v37, v101
	s_waitcnt lgkmcnt(0)
	v_lshlrev_b32_e32 v44, 16, v37
	v_fma_mixlo_f16 v37, v55, v38, 0
	v_cvt_f32_f16_e32 v38, v37
	v_exp_f32_e32 v38, v38
	s_nop 0
	v_fma_f32 v38, -v38, v38, 1.0
	v_max_f32_e32 v38, 0, v38
	v_sqrt_f32_e32 v38, v38
	s_nop 0
	v_mul_f32_e32 v38, v39, v38
	v_mul_f32_e32 v38, v38, v44
	v_fmamk_f32 v39, v79, 0xbfb8aa3b, v80
	v_fmamk_f32 v44, v63, 0xbfb8aa3b, v81
	v_min_f32_e32 v39, 0x42700000, v39
	v_min_f32_e32 v44, 0x42700000, v44
	v_exp_f32_e32 v39, v39
	v_exp_f32_e32 v44, v44
	v_add_f32_e32 v39, 1.0, v39
	v_add_f32_e32 v44, 1.0, v44
	v_mul_f32_e32 v45, v39, v44
	v_rcp_f32_e32 v45, v45
	s_nop 0
	v_mul_f32_e32 v44, v44, v45
	v_mul_f32_e32 v45, v39, v45
	v_mov_b32_e32 v39, v102
	s_waitcnt lgkmcnt(0)
	v_lshlrev_b32_e32 v46, 16, v39
	v_fma_mixlo_f16 v39, v55, v44, 0
	v_cvt_f32_f16_e32 v44, v39
	v_exp_f32_e32 v44, v44
	s_nop 0
	v_fma_f32 v44, -v44, v44, 1.0
	v_max_f32_e32 v44, 0, v44
	v_sqrt_f32_e32 v44, v44
	s_nop 0
	v_mul_f32_e32 v44, v45, v44
	v_mul_f32_e32 v44, v44, v46
	v_fmamk_f32 v45, v72, 0xbfb8aa3b, v80
	v_fmamk_f32 v46, v56, 0xbfb8aa3b, v81
	v_min_f32_e32 v45, 0x42700000, v45
	v_min_f32_e32 v46, 0x42700000, v46
	v_exp_f32_e32 v45, v45
	v_exp_f32_e32 v46, v46
	v_add_f32_e32 v45, 1.0, v45
	v_add_f32_e32 v46, 1.0, v46
	v_mul_f32_e32 v47, v45, v46
	v_rcp_f32_e32 v47, v47
	s_nop 0
	v_mul_f32_e32 v46, v46, v47
	v_mul_f32_e32 v47, v45, v47
	v_mov_b32_e32 v45, v103
	s_waitcnt lgkmcnt(0)
	v_lshlrev_b32_e32 v52, 16, v45
	v_fma_mixlo_f16 v45, v55, v46, 0
	v_cvt_f32_f16_e32 v46, v45
	v_exp_f32_e32 v46, v46
	s_nop 0
	v_fma_f32 v46, -v46, v46, 1.0
	v_max_f32_e32 v46, 0, v46
	v_sqrt_f32_e32 v46, v46
	s_nop 0
	v_mul_f32_e32 v46, v47, v46
	v_mul_f32_e32 v46, v46, v52
	v_fmamk_f32 v47, v73, 0xbfb8aa3b, v80
	v_fmamk_f32 v52, v57, 0xbfb8aa3b, v81
	v_min_f32_e32 v47, 0x42700000, v47
	v_min_f32_e32 v52, 0x42700000, v52
	v_exp_f32_e32 v47, v47
	v_exp_f32_e32 v52, v52
	v_mul_f32_e32 v73, 0xbfb8aa3b, v173
	v_fmamk_f32 v48, v48, 0xbfb8aa3b, v73
	v_add_f32_e32 v47, 1.0, v47
	v_add_f32_e32 v52, 1.0, v52
	v_mul_f32_e32 v53, v47, v52
	v_rcp_f32_e32 v53, v53
	v_min_f32_e32 v48, 0x42700000, v48
	v_exp_f32_e32 v48, v48
	v_fmamk_f32 v49, v49, 0xbfb8aa3b, v73
	v_mul_f32_e32 v52, v52, v53
	v_mul_f32_e32 v53, v47, v53
	v_mov_b32_e32 v47, v104
	v_add_f32_e32 v48, 1.0, v48
	v_min_f32_e32 v49, 0x42700000, v49
	v_exp_f32_e32 v49, v49
	v_fmamk_f32 v50, v50, 0xbfb8aa3b, v73
	s_waitcnt lgkmcnt(0)
	v_lshlrev_b32_e32 v54, 16, v47
	v_fma_mixlo_f16 v47, v55, v52, 0
	v_cvt_f32_f16_e32 v52, v47
	v_add_f32_e32 v49, 1.0, v49
	v_min_f32_e32 v50, 0x42700000, v50
	v_exp_f32_e32 v50, v50
	v_exp_f32_e32 v52, v52
	v_fmamk_f32 v51, v51, 0xbfb8aa3b, v73
	v_min_f32_e32 v51, 0x42700000, v51
	v_add_f32_e32 v50, 1.0, v50
	v_fma_f32 v52, -v52, v52, 1.0
	v_max_f32_e32 v52, 0, v52
	v_sqrt_f32_e32 v52, v52
	v_exp_f32_e32 v51, v51
	v_fmamk_f32 v40, v40, 0xbfb8aa3b, v73
	v_min_f32_e32 v40, 0x42700000, v40
	v_mul_f32_e32 v52, v53, v52
	v_mul_f32_e32 v52, v52, v54
	v_fmamk_f32 v53, v74, 0xbfb8aa3b, v80
	v_fmamk_f32 v54, v58, 0xbfb8aa3b, v81
	v_min_f32_e32 v53, 0x42700000, v53
	v_min_f32_e32 v54, 0x42700000, v54
	v_exp_f32_e32 v53, v53
	v_exp_f32_e32 v54, v54
	v_fmac_f32_e32 v80, 0xbfb8aa3b, v75
	v_fmac_f32_e32 v81, 0xbfb8aa3b, v59
	v_add_f32_e32 v53, 1.0, v53
	v_add_f32_e32 v54, 1.0, v54
	v_mul_f32_e32 v56, v53, v54
	v_rcp_f32_e32 v56, v56
	v_mul_f32_e32 v74, 0xbfb8aa3b, v172
	v_add_f32_e32 v51, 1.0, v51
	v_exp_f32_e32 v40, v40
	v_mul_f32_e32 v54, v54, v56
	v_mul_f32_e32 v56, v53, v56
	v_mov_b32_e32 v53, v105
	v_add_f32_e32 v40, 1.0, v40
	v_fmamk_f32 v41, v41, 0xbfb8aa3b, v73
	v_min_f32_e32 v41, 0x42700000, v41
	v_exp_f32_e32 v41, v41
	s_waitcnt lgkmcnt(0)
	v_lshlrev_b32_e32 v57, 16, v53
	v_fma_mixlo_f16 v53, v55, v54, 0
	v_cvt_f32_f16_e32 v54, v53
	v_add_f32_e32 v41, 1.0, v41
	v_fmamk_f32 v42, v42, 0xbfb8aa3b, v73
	v_min_f32_e32 v42, 0x42700000, v42
	v_exp_f32_e32 v54, v54
	v_exp_f32_e32 v42, v42
	v_fmac_f32_e32 v73, 0xbfb8aa3b, v43
	v_min_f32_e32 v43, 0x42700000, v73
	v_fma_f32 v54, -v54, v54, 1.0
	v_max_f32_e32 v54, 0, v54
	v_sqrt_f32_e32 v54, v54
	v_add_f32_e32 v42, 1.0, v42
	v_exp_f32_e32 v43, v43
	v_mul_f32_e32 v54, v56, v54
	v_mul_f32_e32 v54, v54, v57
	v_min_f32_e32 v56, 0x42700000, v80
	v_min_f32_e32 v57, 0x42700000, v81
	v_exp_f32_e32 v56, v56
	v_exp_f32_e32 v57, v57
	v_add_f32_e32 v43, 1.0, v43
	v_add_f32_e32 v56, 1.0, v56
	v_add_f32_e32 v57, 1.0, v57
	v_mul_f32_e32 v58, v56, v57
	v_rcp_f32_e32 v58, v58
	s_nop 0
	v_mul_f32_e32 v57, v57, v58
	v_fma_mixlo_f16 v55, v55, v57, 0
	v_cvt_f32_f16_e32 v57, v55
	v_mul_f32_e32 v56, v56, v58
	v_mov_b32_e32 v58, v106
	v_exp_f32_e32 v57, v57
	s_waitcnt lgkmcnt(0)
	v_lshlrev_b32_e32 v58, 16, v58
	v_fma_f32 v57, -v57, v57, 1.0
	v_max_f32_e32 v57, 0, v57
	v_sqrt_f32_e32 v57, v57
	s_nop 0
	v_mul_f32_e32 v56, v56, v57
	v_mul_f32_e32 v57, 0xbfb8aa3b, v171
	v_exp_f32_e32 v57, v57
	v_mul_f32_e32 v56, v56, v58
	v_add_f32_e32 v57, 1.0, v57
	v_log_f32_e32 v57, v57
	s_nop 0
	v_mul_f32_e32 v57, 0x3f317218, v57
	v_mul_f32_e32 v72, 0xc138aa3b, v57
	v_fmamk_f32 v57, v68, 0xbfb8aa3b, v74
	v_min_f32_e32 v57, 0x42700000, v57
	v_exp_f32_e32 v57, v57
	s_nop 0
	v_add_f32_e32 v57, 1.0, v57
	v_mul_f32_e32 v58, v57, v48
	v_rcp_f32_e32 v58, v58
	s_nop 0
	v_mul_f32_e32 v48, v48, v58
	v_fma_mixlo_f16 v48, v72, v48, 0
	v_cvt_f32_f16_e32 v59, v48
	v_mul_f32_e32 v57, v57, v58
	v_lshlrev_b32_e32 v58, 16, v60
	v_exp_f32_e32 v59, v59
	s_nop 0
	v_fma_f32 v59, -v59, v59, 1.0
	v_max_f32_e32 v59, 0, v59
	v_sqrt_f32_e32 v59, v59
	s_nop 0
	v_mul_f32_e32 v57, v57, v59
	v_mul_f32_e32 v57, v57, v58
	v_fmamk_f32 v58, v69, 0xbfb8aa3b, v74
	v_min_f32_e32 v58, 0x42700000, v58
	v_exp_f32_e32 v58, v58
	s_nop 0
	v_add_f32_e32 v58, 1.0, v58
	v_mul_f32_e32 v59, v58, v49
	v_rcp_f32_e32 v59, v59
	s_nop 0
	v_mul_f32_e32 v49, v49, v59
	v_fma_mixlo_f16 v49, v72, v49, 0
	v_cvt_f32_f16_e32 v60, v49
	v_mul_f32_e32 v58, v58, v59
	v_mov_b32_e32 v59, v107
	v_exp_f32_e32 v60, v60
	s_waitcnt lgkmcnt(0)
	v_lshlrev_b32_e32 v59, 16, v59
	v_fma_f32 v60, -v60, v60, 1.0
	v_max_f32_e32 v60, 0, v60
	v_sqrt_f32_e32 v60, v60
	s_nop 0
	v_mul_f32_e32 v58, v58, v60
	v_mul_f32_e32 v58, v58, v59
	v_fmamk_f32 v59, v70, 0xbfb8aa3b, v74
	v_min_f32_e32 v59, 0x42700000, v59
	v_exp_f32_e32 v59, v59
	s_nop 0
	v_add_f32_e32 v59, 1.0, v59
	v_mul_f32_e32 v60, v59, v50
	v_rcp_f32_e32 v60, v60
	s_nop 0
	v_mul_f32_e32 v50, v50, v60
	v_fma_mixlo_f16 v50, v72, v50, 0
	v_cvt_f32_f16_e32 v61, v50
	v_mul_f32_e32 v59, v59, v60
	v_mov_b32_e32 v60, v108
	v_exp_f32_e32 v61, v61
	s_waitcnt lgkmcnt(0)
	v_lshlrev_b32_e32 v60, 16, v60
	v_fma_f32 v61, -v61, v61, 1.0
	v_max_f32_e32 v61, 0, v61
	v_sqrt_f32_e32 v61, v61
	s_nop 0
	v_mul_f32_e32 v59, v59, v61
	v_mul_f32_e32 v59, v59, v60
	v_fmamk_f32 v60, v71, 0xbfb8aa3b, v74
	v_min_f32_e32 v60, 0x42700000, v60
	v_exp_f32_e32 v60, v60
	s_nop 0
	v_add_f32_e32 v60, 1.0, v60
	v_mul_f32_e32 v61, v60, v51
	v_rcp_f32_e32 v61, v61
	s_nop 0
	v_mul_f32_e32 v51, v51, v61
	v_fma_mixlo_f16 v51, v72, v51, 0
	v_cvt_f32_f16_e32 v62, v51
	v_mul_f32_e32 v60, v60, v61
	v_mov_b32_e32 v61, v109
	v_exp_f32_e32 v62, v62
	s_waitcnt lgkmcnt(0)
	v_lshlrev_b32_e32 v61, 16, v61
	v_fma_f32 v62, -v62, v62, 1.0
	v_max_f32_e32 v62, 0, v62
	v_sqrt_f32_e32 v62, v62
	s_nop 0
	v_mul_f32_e32 v60, v60, v62
	v_mul_f32_e32 v60, v60, v61
	v_fmamk_f32 v61, v64, 0xbfb8aa3b, v74
	v_min_f32_e32 v61, 0x42700000, v61
	v_exp_f32_e32 v61, v61
	s_nop 0
	v_add_f32_e32 v61, 1.0, v61
	v_mul_f32_e32 v62, v61, v40
	v_rcp_f32_e32 v62, v62
	s_nop 0
	v_mul_f32_e32 v40, v40, v62
	v_fma_mixlo_f16 v40, v72, v40, 0
	v_cvt_f32_f16_e32 v63, v40
	v_mul_f32_e32 v61, v61, v62
	v_mov_b32_e32 v62, v110
	v_exp_f32_e32 v63, v63
	s_waitcnt lgkmcnt(0)
	v_lshlrev_b32_e32 v62, 16, v62
	v_fma_f32 v63, -v63, v63, 1.0
	v_max_f32_e32 v63, 0, v63
	v_sqrt_f32_e32 v63, v63
	s_nop 0
	v_mul_f32_e32 v61, v61, v63
	v_mul_f32_e32 v61, v61, v62
	v_fmamk_f32 v62, v65, 0xbfb8aa3b, v74
	v_min_f32_e32 v62, 0x42700000, v62
	v_exp_f32_e32 v62, v62
	s_nop 0
	v_add_f32_e32 v62, 1.0, v62
	v_mul_f32_e32 v63, v62, v41
	v_rcp_f32_e32 v63, v63
	s_nop 0
	v_mul_f32_e32 v41, v41, v63
	v_fma_mixlo_f16 v41, v72, v41, 0
	v_cvt_f32_f16_e32 v64, v41
	v_mul_f32_e32 v62, v62, v63
	v_mov_b32_e32 v63, v111
	v_exp_f32_e32 v64, v64
	s_waitcnt lgkmcnt(0)
	v_lshlrev_b32_e32 v63, 16, v63
	v_fma_f32 v64, -v64, v64, 1.0
	v_max_f32_e32 v64, 0, v64
	v_sqrt_f32_e32 v64, v64
	s_nop 0
	v_mul_f32_e32 v62, v62, v64
	v_mul_f32_e32 v62, v62, v63
	v_fmamk_f32 v63, v66, 0xbfb8aa3b, v74
	v_min_f32_e32 v63, 0x42700000, v63
	v_exp_f32_e32 v63, v63
	v_fmac_f32_e32 v74, 0xbfb8aa3b, v67
	v_mul_f32_e32 v67, 0xbfb8aa3b, v169
	v_fmamk_f32 v24, v24, 0xbfb8aa3b, v67
	v_add_f32_e32 v63, 1.0, v63
	v_mul_f32_e32 v64, v63, v42
	v_rcp_f32_e32 v64, v64
	v_min_f32_e32 v24, 0x42700000, v24
	v_exp_f32_e32 v24, v24
	v_fmamk_f32 v25, v25, 0xbfb8aa3b, v67
	v_mul_f32_e32 v42, v42, v64
	v_fma_mixlo_f16 v42, v72, v42, 0
	v_cvt_f32_f16_e32 v65, v42
	v_mul_f32_e32 v63, v63, v64
	v_mov_b32_e32 v64, v112
	v_add_f32_e32 v68, 1.0, v24
	v_exp_f32_e32 v65, v65
	v_min_f32_e32 v25, 0x42700000, v25
	v_exp_f32_e32 v25, v25
	s_waitcnt lgkmcnt(0)
	v_lshlrev_b32_e32 v64, 16, v64
	v_fma_f32 v65, -v65, v65, 1.0
	v_max_f32_e32 v65, 0, v65
	v_sqrt_f32_e32 v65, v65
	v_fmamk_f32 v26, v26, 0xbfb8aa3b, v67
	v_fmamk_f32 v27, v27, 0xbfb8aa3b, v67
	v_fmamk_f32 v16, v16, 0xbfb8aa3b, v67
	v_mul_f32_e32 v63, v63, v65
	v_mul_f32_e32 v63, v63, v64
	v_min_f32_e32 v64, 0x42700000, v74
	v_exp_f32_e32 v64, v64
	v_fmamk_f32 v17, v17, 0xbfb8aa3b, v67
	v_fmamk_f32 v18, v18, 0xbfb8aa3b, v67
	v_fmac_f32_e32 v67, 0xbfb8aa3b, v19
	v_add_f32_e32 v64, 1.0, v64
	v_mul_f32_e32 v65, v64, v43
	v_rcp_f32_e32 v65, v65
	v_add_f32_e32 v25, 1.0, v25
	v_min_f32_e32 v19, 0x42700000, v67
	v_exp_f32_e32 v19, v19
	v_mul_f32_e32 v43, v43, v65
	v_fma_mixlo_f16 v43, v72, v43, 0
	v_cvt_f32_f16_e32 v66, v43
	v_mul_f32_e32 v64, v64, v65
	v_mov_b32_e32 v65, v113
	v_add_f32_e32 v19, 1.0, v19
	v_exp_f32_e32 v66, v66
	v_min_f32_e32 v26, 0x42700000, v26
	v_exp_f32_e32 v26, v26
	v_min_f32_e32 v27, 0x42700000, v27
	v_fma_f32 v66, -v66, v66, 1.0
	v_max_f32_e32 v66, 0, v66
	v_sqrt_f32_e32 v66, v66
	v_add_f32_e32 v26, 1.0, v26
	v_exp_f32_e32 v27, v27
	v_min_f32_e32 v16, 0x42700000, v16
	v_mul_f32_e32 v64, v64, v66
	v_mul_f32_e32 v66, 0xbfb8aa3b, v170
	v_fmamk_f32 v24, v28, 0xbfb8aa3b, v66
	v_min_f32_e32 v24, 0x42700000, v24
	v_exp_f32_e32 v24, v24
	v_fmamk_f32 v29, v29, 0xbfb8aa3b, v66
	v_min_f32_e32 v29, 0x42700000, v29
	v_exp_f32_e32 v29, v29
	v_add_f32_e32 v24, 1.0, v24
	v_mul_f32_e32 v28, v68, v24
	v_rcp_f32_e32 v28, v28
	v_fmamk_f32 v30, v30, 0xbfb8aa3b, v66
	v_fmamk_f32 v31, v31, 0xbfb8aa3b, v66
	v_fmamk_f32 v20, v20, 0xbfb8aa3b, v66
	v_mul_f32_e32 v24, v24, v28
	v_mul_f32_e32 v28, v68, v28
	v_mov_b32_e32 v68, v114
	s_waitcnt lgkmcnt(1)
	v_lshlrev_b32_e32 v65, 16, v65
	v_mul_f32_e32 v64, v64, v65
	v_mul_f32_e32 v65, 0xbfb8aa3b, v168
	v_exp_f32_e32 v65, v65
	v_fmamk_f32 v21, v21, 0xbfb8aa3b, v66
	v_fmamk_f32 v22, v22, 0xbfb8aa3b, v66
	v_fmac_f32_e32 v66, 0xbfb8aa3b, v23
	v_add_f32_e32 v65, 1.0, v65
	v_log_f32_e32 v65, v65
	s_waitcnt lgkmcnt(0)
	v_lshlrev_b32_e32 v68, 16, v68
	v_add_f32_e32 v29, 1.0, v29
	v_min_f32_e32 v23, 0x42700000, v66
	v_mul_f32_e32 v65, 0x3f317218, v65
	v_mul_f32_e32 v65, 0xc138aa3b, v65
	v_fma_mixlo_f16 v24, v65, v24, 0
	v_cvt_f32_f16_e32 v69, v24
	v_exp_f32_e32 v23, v23
	v_min_f32_e32 v30, 0x42700000, v30
	v_exp_f32_e32 v30, v30
	v_exp_f32_e32 v69, v69
	v_add_f32_e32 v23, 1.0, v23
	v_mul_f32_e32 v66, v19, v23
	v_rcp_f32_e32 v66, v66
	v_fma_f32 v69, -v69, v69, 1.0
	v_max_f32_e32 v69, 0, v69
	v_sqrt_f32_e32 v69, v69
	v_mul_f32_e32 v23, v23, v66
	v_mul_f32_e32 v66, v19, v66
	v_mov_b32_e32 v19, v115
	v_mul_f32_e32 v28, v28, v69
	v_mul_f32_e32 v28, v28, v68
	v_mul_f32_e32 v68, v25, v29
	v_rcp_f32_e32 v68, v68
	v_add_f32_e32 v30, 1.0, v30
	v_min_f32_e32 v31, 0x42700000, v31
	v_exp_f32_e32 v31, v31
	v_mul_f32_e32 v29, v29, v68
	v_mul_f32_e32 v68, v25, v68
	v_mov_b32_e32 v25, v116
	v_add_f32_e32 v27, 1.0, v27
	v_add_f32_e32 v31, 1.0, v31
	v_min_f32_e32 v20, 0x42700000, v20
	v_exp_f32_e32 v16, v16
	s_waitcnt lgkmcnt(0)
	v_lshlrev_b32_e32 v69, 16, v25
	v_fma_mixlo_f16 v25, v65, v29, 0
	v_cvt_f32_f16_e32 v29, v25
	v_exp_f32_e32 v20, v20
	v_add_f32_e32 v16, 1.0, v16
	v_min_f32_e32 v17, 0x42700000, v17
	v_exp_f32_e32 v29, v29
	v_add_f32_e32 v20, 1.0, v20
	v_min_f32_e32 v21, 0x42700000, v21
	v_exp_f32_e32 v17, v17
	v_fma_f32 v29, -v29, v29, 1.0
	v_max_f32_e32 v29, 0, v29
	v_sqrt_f32_e32 v29, v29
	v_exp_f32_e32 v21, v21
	v_add_f32_e32 v17, 1.0, v17
	v_min_f32_e32 v18, 0x42700000, v18
	v_mul_f32_e32 v29, v68, v29
	v_mul_f32_e32 v68, v26, v30
	v_rcp_f32_e32 v68, v68
	v_mul_f32_e32 v29, v29, v69
	v_add_f32_e32 v21, 1.0, v21
	v_min_f32_e32 v22, 0x42700000, v22
	v_mul_f32_e32 v30, v30, v68
	v_mul_f32_e32 v68, v26, v68
	v_mov_b32_e32 v26, v117
	v_exp_f32_e32 v18, v18
	v_exp_f32_e32 v22, v22
	v_lshlrev_b32_e32 v67, 16, v19
	v_fma_mixlo_f16 v19, v65, v23, 0
	s_waitcnt lgkmcnt(0)
	v_lshlrev_b32_e32 v69, 16, v26
	v_fma_mixlo_f16 v26, v65, v30, 0
	v_cvt_f32_f16_e32 v30, v26
	v_add_f32_e32 v18, 1.0, v18
	v_add_f32_e32 v22, 1.0, v22
	v_cvt_f32_f16_e32 v23, v19
	v_exp_f32_e32 v30, v30
	v_and_b32_e32 v24, 0xffff, v24
	v_exp_f32_e32 v23, v23
	v_fma_f32 v30, -v30, v30, 1.0
	v_max_f32_e32 v30, 0, v30
	v_sqrt_f32_e32 v30, v30
	v_fma_f32 v23, -v23, v23, 1.0
	v_max_f32_e32 v23, 0, v23
	v_sqrt_f32_e32 v23, v23
	v_mul_f32_e32 v30, v68, v30
	v_mul_f32_e32 v68, v27, v31
	v_rcp_f32_e32 v68, v68
	v_mul_f32_e32 v30, v30, v69
	v_mul_f32_e32 v23, v66, v23
	v_mul_f32_e32 v23, v23, v67
	v_mul_f32_e32 v31, v31, v68
	v_mul_f32_e32 v68, v27, v68
	v_mov_b32_e32 v27, v118
	v_mul_f32_e32 v67, 0xbfb8aa3b, v165
	v_mul_f32_e32 v66, 0xbfb8aa3b, v167
	v_fmamk_f32 v8, v8, 0xbfb8aa3b, v67
	v_fmamk_f32 v12, v12, 0xbfb8aa3b, v66
	s_waitcnt lgkmcnt(0)
	v_lshlrev_b32_e32 v69, 16, v27
	v_fma_mixlo_f16 v27, v65, v31, 0
	v_cvt_f32_f16_e32 v31, v27
	v_min_f32_e32 v8, 0x42700000, v8
	v_min_f32_e32 v12, 0x42700000, v12
	v_exp_f32_e32 v8, v8
	v_exp_f32_e32 v31, v31
	v_exp_f32_e32 v12, v12
	v_fmamk_f32 v9, v9, 0xbfb8aa3b, v67
	v_add_f32_e32 v8, 1.0, v8
	v_fma_f32 v31, -v31, v31, 1.0
	v_max_f32_e32 v31, 0, v31
	v_sqrt_f32_e32 v31, v31
	v_add_f32_e32 v12, 1.0, v12
	v_min_f32_e32 v9, 0x42700000, v9
	v_exp_f32_e32 v9, v9
	v_mul_f32_e32 v31, v68, v31
	v_mul_f32_e32 v68, v16, v20
	v_rcp_f32_e32 v68, v68
	v_mul_f32_e32 v31, v31, v69
	v_fmamk_f32 v10, v10, 0xbfb8aa3b, v67
	v_fmamk_f32 v14, v14, 0xbfb8aa3b, v66
	v_mul_f32_e32 v20, v20, v68
	v_mul_f32_e32 v68, v16, v68
	v_mov_b32_e32 v16, v119
	v_fmamk_f32 v11, v11, 0xbfb8aa3b, v67
	v_fmamk_f32 v15, v15, 0xbfb8aa3b, v66
	v_fmamk_f32 v0, v0, 0xbfb8aa3b, v67
	v_fmamk_f32 v4, v4, 0xbfb8aa3b, v66
	s_waitcnt lgkmcnt(0)
	v_lshlrev_b32_e32 v69, 16, v16
	v_fma_mixlo_f16 v16, v65, v20, 0
	v_cvt_f32_f16_e32 v20, v16
	v_fmamk_f32 v1, v1, 0xbfb8aa3b, v67
	v_fmamk_f32 v5, v5, 0xbfb8aa3b, v66
	v_fmamk_f32 v2, v2, 0xbfb8aa3b, v67
	v_exp_f32_e32 v20, v20
	v_fmamk_f32 v6, v6, 0xbfb8aa3b, v66
	v_fmac_f32_e32 v67, 0xbfb8aa3b, v3
	v_min_f32_e32 v3, 0x42700000, v67
	v_fma_f32 v20, -v20, v20, 1.0
	v_max_f32_e32 v20, 0, v20
	v_sqrt_f32_e32 v20, v20
	v_exp_f32_e32 v3, v3
	v_min_f32_e32 v10, 0x42700000, v10
	v_min_f32_e32 v14, 0x42700000, v14
	v_mul_f32_e32 v20, v68, v20
	v_mul_f32_e32 v68, v17, v21
	v_rcp_f32_e32 v68, v68
	v_mul_f32_e32 v20, v20, v69
	v_add_f32_e32 v3, 1.0, v3
	v_exp_f32_e32 v10, v10
	v_mul_f32_e32 v21, v21, v68
	v_mul_f32_e32 v68, v17, v68
	v_mov_b32_e32 v17, v142
	v_exp_f32_e32 v14, v14
	v_add_f32_e32 v10, 1.0, v10
	v_min_f32_e32 v11, 0x42700000, v11
	v_min_f32_e32 v15, 0x42700000, v15
	s_waitcnt lgkmcnt(0)
	v_lshlrev_b32_e32 v69, 16, v17
	v_fma_mixlo_f16 v17, v65, v21, 0
	v_cvt_f32_f16_e32 v21, v17
	v_add_f32_e32 v14, 1.0, v14
	v_exp_f32_e32 v11, v11
	v_exp_f32_e32 v15, v15
	v_exp_f32_e32 v21, v21
	v_min_f32_e32 v0, 0x42700000, v0
	v_add_f32_e32 v11, 1.0, v11
	v_add_f32_e32 v15, 1.0, v15
	v_fma_f32 v21, -v21, v21, 1.0
	v_max_f32_e32 v21, 0, v21
	v_sqrt_f32_e32 v21, v21
	v_min_f32_e32 v4, 0x42700000, v4
	v_exp_f32_e32 v0, v0
	v_exp_f32_e32 v4, v4
	v_mul_f32_e32 v21, v68, v21
	v_mul_f32_e32 v68, v18, v22
	v_rcp_f32_e32 v68, v68
	v_mul_f32_e32 v21, v21, v69
	v_add_f32_e32 v0, 1.0, v0
	v_add_f32_e32 v4, 1.0, v4
	v_mul_f32_e32 v22, v22, v68
	v_mul_f32_e32 v68, v18, v68
	v_mov_b32_e32 v18, v143
	v_min_f32_e32 v1, 0x42700000, v1
	v_min_f32_e32 v5, 0x42700000, v5
	v_exp_f32_e32 v1, v1
	v_exp_f32_e32 v5, v5
	s_waitcnt lgkmcnt(0)
	v_lshlrev_b32_e32 v69, 16, v18
	v_fma_mixlo_f16 v18, v65, v22, 0
	v_cvt_f32_f16_e32 v22, v18
	v_mul_f32_e32 v65, 0xbfb8aa3b, v166
	v_exp_f32_e32 v65, v65
	v_add_f32_e32 v1, 1.0, v1
	v_exp_f32_e32 v22, v22
	v_add_f32_e32 v5, 1.0, v5
	v_add_f32_e32 v65, 1.0, v65
	v_log_f32_e32 v65, v65
	v_fma_f32 v22, -v22, v22, 1.0
	v_max_f32_e32 v22, 0, v22
	v_sqrt_f32_e32 v22, v22
	v_mul_f32_e32 v65, 0x3f317218, v65
	v_mul_f32_e32 v65, 0xc138aa3b, v65
	v_min_f32_e32 v2, 0x42700000, v2
	v_mul_f32_e32 v22, v68, v22
	v_mul_f32_e32 v68, v8, v12
	v_rcp_f32_e32 v68, v68
	v_mul_f32_e32 v22, v22, v69
	v_min_f32_e32 v6, 0x42700000, v6
	v_exp_f32_e32 v2, v2
	v_mul_f32_e32 v12, v12, v68
	v_mul_f32_e32 v68, v8, v68
	v_mov_b32_e32 v8, v144
	v_exp_f32_e32 v6, v6
	v_add_f32_e32 v2, 1.0, v2
	v_and_b32_e32 v16, 0xffff, v16
	s_waitcnt lgkmcnt(0)
	v_lshlrev_b32_e32 v69, 16, v8
	v_fma_mixlo_f16 v8, v65, v12, 0
	v_cvt_f32_f16_e32 v12, v8
	v_add_f32_e32 v6, 1.0, v6
	v_and_b32_e32 v8, 0xffff, v8
	v_exp_f32_e32 v12, v12
	s_nop 0
	v_fma_f32 v12, -v12, v12, 1.0
	v_max_f32_e32 v12, 0, v12
	v_sqrt_f32_e32 v12, v12
	s_nop 0
	v_mul_f32_e32 v12, v68, v12
	v_add_f32_e32 v68, 1.0, v9
	v_fmamk_f32 v9, v13, 0xbfb8aa3b, v66
	v_min_f32_e32 v9, 0x42700000, v9
	v_exp_f32_e32 v9, v9
	v_mul_f32_e32 v12, v12, v69
	v_fmac_f32_e32 v66, 0xbfb8aa3b, v7
	v_min_f32_e32 v7, 0x42700000, v66
	v_add_f32_e32 v9, 1.0, v9
	v_mul_f32_e32 v13, v68, v9
	v_rcp_f32_e32 v13, v13
	v_exp_f32_e32 v7, v7
	v_mul_f32_e32 v9, v9, v13
	v_fma_mixlo_f16 v9, v65, v9, 0
	v_cvt_f32_f16_e32 v69, v9
	v_add_f32_e32 v7, 1.0, v7
	v_mul_f32_e32 v13, v68, v13
	v_mov_b32_e32 v68, v145
	v_exp_f32_e32 v69, v69
	v_mul_f32_e32 v66, v3, v7
	v_rcp_f32_e32 v66, v66
	v_fma_f32 v69, -v69, v69, 1.0
	v_max_f32_e32 v69, 0, v69
	v_sqrt_f32_e32 v69, v69
	v_mul_f32_e32 v7, v7, v66
	v_mul_f32_e32 v3, v3, v66
	v_mov_b32_e32 v66, v146
	s_waitcnt lgkmcnt(1)
	v_lshlrev_b32_e32 v68, 16, v68
	v_mul_f32_e32 v13, v13, v69
	v_mul_f32_e32 v13, v13, v68
	v_mul_f32_e32 v68, v10, v14
	v_rcp_f32_e32 v68, v68
	v_fma_mixlo_f16 v7, v65, v7, 0
	s_waitcnt lgkmcnt(0)
	v_lshlrev_b32_e32 v66, 16, v66
	v_mul_f32_e32 v14, v14, v68
	v_mul_f32_e32 v68, v10, v68
	v_mov_b32_e32 v10, v147
	s_waitcnt lgkmcnt(0)
	v_lshlrev_b32_e32 v69, 16, v10
	v_fma_mixlo_f16 v10, v65, v14, 0
	v_cvt_f32_f16_e32 v14, v10
	v_exp_f32_e32 v14, v14
	s_nop 0
	v_fma_f32 v14, -v14, v14, 1.0
	v_max_f32_e32 v14, 0, v14
	v_sqrt_f32_e32 v14, v14
	s_nop 0
	v_mul_f32_e32 v14, v68, v14
	v_mul_f32_e32 v68, v11, v15
	v_rcp_f32_e32 v68, v68
	v_mul_f32_e32 v14, v14, v69
	v_mul_f32_e32 v15, v15, v68
	v_mul_f32_e32 v68, v11, v68
	v_mov_b32_e32 v11, v148
	s_waitcnt lgkmcnt(0)
	v_lshlrev_b32_e32 v69, 16, v11
	v_fma_mixlo_f16 v11, v65, v15, 0
	v_cvt_f32_f16_e32 v15, v11
	v_exp_f32_e32 v15, v15
	s_nop 0
	v_fma_f32 v15, -v15, v15, 1.0
	v_max_f32_e32 v15, 0, v15
	v_sqrt_f32_e32 v15, v15
	s_nop 0
	v_mul_f32_e32 v15, v68, v15
	v_mul_f32_e32 v68, v0, v4
	v_rcp_f32_e32 v68, v68
	v_mul_f32_e32 v15, v15, v69
	v_mul_f32_e32 v4, v4, v68
	v_mul_f32_e32 v68, v0, v68
	v_mov_b32_e32 v0, v149
	s_waitcnt lgkmcnt(0)
	v_lshlrev_b32_e32 v69, 16, v0
	v_fma_mixlo_f16 v0, v65, v4, 0
	v_cvt_f32_f16_e32 v4, v0
	v_and_b32_e32 v0, 0xffff, v0
	v_exp_f32_e32 v4, v4
	s_nop 0
	v_fma_f32 v4, -v4, v4, 1.0
	v_max_f32_e32 v4, 0, v4
	v_sqrt_f32_e32 v4, v4
	s_nop 0
	v_mul_f32_e32 v4, v68, v4
	v_mul_f32_e32 v68, v1, v5
	v_rcp_f32_e32 v68, v68
	v_mul_f32_e32 v4, v4, v69
	v_mul_f32_e32 v5, v5, v68
	v_mul_f32_e32 v68, v1, v68
	v_mov_b32_e32 v1, v150
	s_waitcnt lgkmcnt(0)
	v_lshlrev_b32_e32 v69, 16, v1
	v_fma_mixlo_f16 v1, v65, v5, 0
	v_cvt_f32_f16_e32 v5, v1
	v_exp_f32_e32 v5, v5
	s_nop 0
	v_fma_f32 v5, -v5, v5, 1.0
	v_max_f32_e32 v5, 0, v5
	v_sqrt_f32_e32 v5, v5
	s_nop 0
	v_mul_f32_e32 v5, v68, v5
	v_mul_f32_e32 v68, v2, v6
	v_rcp_f32_e32 v68, v68
	v_mul_f32_e32 v5, v5, v69
	v_mul_f32_e32 v6, v6, v68
	v_mul_f32_e32 v68, v2, v68
	v_mov_b32_e32 v2, v151
	s_waitcnt lgkmcnt(0)
	s_barrier
	v_cvt_pk_bf16_f32 v34, v185, v34
	v_lshlrev_b32_e32 v69, 16, v2
	v_fma_mixlo_f16 v2, v65, v6, 0
	v_cvt_f32_f16_e32 v65, v7
	v_and_or_b32 v33, v34, s69, v33
	v_cvt_f32_f16_e32 v6, v2
	v_exp_f32_e32 v65, v65
	v_exp_f32_e32 v6, v6
	v_fma_f32 v65, -v65, v65, 1.0
	v_max_f32_e32 v65, 0, v65
	v_sqrt_f32_e32 v65, v65
	v_fma_f32 v6, -v6, v6, 1.0
	v_max_f32_e32 v6, 0, v6
	v_sqrt_f32_e32 v6, v6
	v_mul_f32_e32 v3, v3, v65
	v_or_b32_e32 v65, v164, v163
	v_lshlrev_b32_e32 v34, 2, v65
	v_add3_u32 v32, s14, v32, v34
	ds_write_b32 v32, v33
	v_and_b32_e32 v33, 0xffff, v35
	v_cvt_pk_bf16_f32 v34, v185, v36
	v_mul_f32_e32 v6, v68, v6
	v_and_or_b32 v33, v34, s69, v33
	ds_write_b32 v32, v33 offset:1024
	v_and_b32_e32 v33, 0xffff, v37
	v_cvt_pk_bf16_f32 v34, v185, v38
	v_mul_f32_e32 v6, v6, v69
	v_and_or_b32 v33, v34, s69, v33
	ds_write_b32 v32, v33 offset:2048
	v_and_b32_e32 v33, 0xffff, v39
	v_cvt_pk_bf16_f32 v34, v185, v44
	v_mul_f32_e32 v3, v3, v66
	v_and_or_b32 v33, v34, s69, v33
	ds_write_b32 v32, v33 offset:3072
	v_and_b32_e32 v33, 0xffff, v45
	v_cvt_pk_bf16_f32 v34, v185, v46
	s_nop 0
	v_and_or_b32 v33, v34, s69, v33
	ds_write_b32 v32, v33 offset:16384
	v_and_b32_e32 v33, 0xffff, v47
	v_cvt_pk_bf16_f32 v34, v185, v52
	s_nop 0
	v_and_or_b32 v33, v34, s69, v33
	ds_write_b32 v32, v33 offset:17408
	v_and_b32_e32 v33, 0xffff, v53
	v_cvt_pk_bf16_f32 v34, v185, v54
	s_nop 0
	v_and_or_b32 v33, v34, s69, v33
	ds_write_b32 v32, v33 offset:18432
	v_and_b32_e32 v33, 0xffff, v55
	v_cvt_pk_bf16_f32 v34, v185, v56
	s_nop 0
	v_and_or_b32 v33, v34, s69, v33
	ds_write_b32 v32, v33 offset:19456
	v_and_b32_e32 v33, 0xffff, v48
	v_cvt_pk_bf16_f32 v34, v185, v57
	s_nop 0
	v_and_or_b32 v33, v34, s69, v33
	ds_write_b32 v32, v33 offset:64
	v_and_b32_e32 v33, 0xffff, v49
	v_cvt_pk_bf16_f32 v34, v185, v58
	s_nop 0
	v_and_or_b32 v33, v34, s69, v33
	ds_write_b32 v32, v33 offset:1088
	v_and_b32_e32 v33, 0xffff, v50
	v_cvt_pk_bf16_f32 v34, v185, v59
	s_nop 0
	v_and_or_b32 v33, v34, s69, v33
	ds_write_b32 v32, v33 offset:2112
	v_and_b32_e32 v33, 0xffff, v51
	v_cvt_pk_bf16_f32 v34, v185, v60
	s_nop 0
	v_and_or_b32 v33, v34, s69, v33
	ds_write_b32 v32, v33 offset:3136
	v_and_b32_e32 v33, 0xffff, v40
	v_cvt_pk_bf16_f32 v34, v185, v61
	s_nop 0
	v_and_or_b32 v33, v34, s69, v33
	ds_write_b32 v32, v33 offset:16448
	v_and_b32_e32 v33, 0xffff, v41
	v_cvt_pk_bf16_f32 v34, v185, v62
	s_nop 0
	v_and_or_b32 v33, v34, s69, v33
	ds_write_b32 v32, v33 offset:17472
	v_and_b32_e32 v33, 0xffff, v42
	v_cvt_pk_bf16_f32 v34, v185, v63
	s_nop 0
	v_and_or_b32 v33, v34, s69, v33
	ds_write_b32 v32, v33 offset:18496
	v_and_b32_e32 v33, 0xffff, v43
	v_cvt_pk_bf16_f32 v34, v185, v64
	s_nop 0
	v_and_or_b32 v33, v34, s69, v33
	ds_write_b32 v32, v33 offset:19520
	v_cvt_pk_bf16_f32 v28, v185, v28
	s_nop 0
	v_and_or_b32 v24, v28, s69, v24
	ds_write_b32 v32, v24 offset:128
	v_and_b32_e32 v24, 0xffff, v25
	v_cvt_pk_bf16_f32 v25, v185, v29
	s_nop 0
	v_and_or_b32 v24, v25, s69, v24
	ds_write_b32 v32, v24 offset:1152
	v_and_b32_e32 v24, 0xffff, v26
	v_cvt_pk_bf16_f32 v25, v185, v30
	s_nop 0
	v_and_or_b32 v24, v25, s69, v24
	ds_write_b32 v32, v24 offset:2176
	v_and_b32_e32 v24, 0xffff, v27
	v_cvt_pk_bf16_f32 v25, v185, v31
	s_nop 0
	v_and_or_b32 v24, v25, s69, v24
	ds_write_b32 v32, v24 offset:3200
	v_cvt_pk_bf16_f32 v20, v185, v20
	s_nop 0
	v_and_or_b32 v16, v20, s69, v16
	ds_write_b32 v32, v16 offset:16512
	v_and_b32_e32 v16, 0xffff, v17
	v_cvt_pk_bf16_f32 v17, v185, v21
	s_nop 0
	v_and_or_b32 v16, v17, s69, v16
	ds_write_b32 v32, v16 offset:17536
	v_and_b32_e32 v16, 0xffff, v18
	v_cvt_pk_bf16_f32 v17, v185, v22
	s_nop 0
	v_and_or_b32 v16, v17, s69, v16
	ds_write_b32 v32, v16 offset:18560
	v_and_b32_e32 v16, 0xffff, v19
	v_cvt_pk_bf16_f32 v17, v185, v23
	s_nop 0
	v_and_or_b32 v16, v17, s69, v16
	ds_write_b32 v32, v16 offset:19584
	v_cvt_pk_bf16_f32 v12, v185, v12
	s_nop 0
	v_and_or_b32 v8, v12, s69, v8
	ds_write_b32 v32, v8 offset:192
	v_and_b32_e32 v8, 0xffff, v9
	v_cvt_pk_bf16_f32 v9, v185, v13
	s_nop 0
	v_and_or_b32 v8, v9, s69, v8
	ds_write_b32 v32, v8 offset:1216
	v_and_b32_e32 v8, 0xffff, v10
	v_cvt_pk_bf16_f32 v9, v185, v14
	s_nop 0
	v_and_or_b32 v8, v9, s69, v8
	ds_write_b32 v32, v8 offset:2240
	v_and_b32_e32 v8, 0xffff, v11
	v_cvt_pk_bf16_f32 v9, v185, v15
	s_nop 0
	v_and_or_b32 v8, v9, s69, v8
	ds_write_b32 v32, v8 offset:3264
	v_cvt_pk_bf16_f32 v4, v185, v4
	s_nop 0
	v_and_or_b32 v0, v4, s69, v0
	ds_write_b32 v32, v0 offset:16576
	v_and_b32_e32 v0, 0xffff, v1
	v_cvt_pk_bf16_f32 v1, v185, v5
	s_nop 0
	v_and_or_b32 v0, v1, s69, v0
	ds_write_b32 v32, v0 offset:17600
	v_and_b32_e32 v0, 0xffff, v2
	v_cvt_pk_bf16_f32 v1, v185, v6
	s_nop 0
	v_and_or_b32 v0, v1, s69, v0
	ds_write_b32 v32, v0 offset:18624
	v_and_b32_e32 v0, 0xffff, v7
	v_cvt_pk_bf16_f32 v1, v185, v3
	s_nop 0
	v_and_or_b32 v0, v1, s69, v0
	ds_write_b32 v32, v0 offset:19648
	s_waitcnt lgkmcnt(0)
	s_barrier
	s_and_saveexec_b64 s[12:13], vcc
	s_cbranch_execz .LBB0_668
	v_lshl_add_u32 v2, v162, 2, s14
	v_mov_b32_e32 v1, 0
	v_mov_b32_e32 v0, 1.0
	s_mov_b32 s14, 0
